# outproj phase: per-XCD dynamic item queues as in merge (the 8 N-tiles of an M-tile share one XCD's L2 for the ACC row tile)
# speedup vs baseline: 1.0284x; 1.0133x over previous
; DI void phase_outproj(const Params& p, int l, char* smem, int tid) {
;     ...
;   const bool dyn = (l == 0);
;   unsigned* qc = p.bar + 4096 + 384;
;   for (int it = (dyn ? fetch_item(qc, smem) : (int)blockIdx.x); it < 272 * 8; it = (dyn ? fetch_item(qc, smem) : it + (int)gridDim.x)) {
;     const int mt = it >> 3, nt = it & 7, m0 = mt * 128, n0 = nt * 128;
;     if (l == 1 && (mt % 34) < 2) continue;
;     f32x16 acc[2][2]; zero_acc<2>(acc);
;     gemm_main<2>(ACC + (size_t)m0 * 1024, 1024, p.WtOut + (size_t)l * 1024 * 1024 + (size_t)n0 * 1024, 1024, 1024, acc, s, tid);
;     u16* O = p.G;
; #pragma unroll
;     for (int mb = 0; mb < 2; mb++)
; #pragma unroll
;       for (int nb = 0; nb < 2; nb++) {
;         const int rowb = m0 + wm * 64 + mb * 32, col = n0 + wn * 64 + nb * 32 + r;
;         const int b = rowb / SEQA, pos0 = rowb % SEQA;
;         const float gate = p.mod[((size_t)l * 9 + ((pos0 < CTXL) ? 8 : b)) * 3072 + 2048 + col];
.Lop_item:
	s_barrier
	s_cmp_eq_u32 s10, 0
	s_cbranch_scc0 .Lopx_wait
	s_mov_b64 s[6:7], exec
	s_mov_b64 exec, 1
	s_getreg_b32 s8, hwreg(HW_REG_XCC_ID, 0, 4)
	s_lshl_b32 s8, s8, 8
	s_lshl_b32 s9, s18, 11
	s_add_u32 s8, s8, s9
	s_add_u32 s8, s8, 0x1da5f000
	s_add_u32 s8, s96, s8
	s_addc_u32 s9, s97, 0
	v_mov_b32_e32 v112, 1
	v_mov_b32_e32 v113, 0
	global_atomic_add v114, v113, v112, s[8:9] sc0
	v_mov_b32_e32 v115, 0x125f0
	s_waitcnt vmcnt(0)
	ds_write_b32 v115, v114
	s_waitcnt lgkmcnt(0)
	s_mov_b64 exec, s[6:7]
.Lopx_wait:
	s_barrier
	v_mov_b32_e32 v115, 0x125f0
	ds_read_b32 v114, v115
	s_waitcnt lgkmcnt(0)
	v_readfirstlane_b32 s12, v114
	s_getreg_b32 s8, hwreg(HW_REG_XCC_ID, 0, 4)
	s_lshr_b32 s6, s12, 3
	s_lshl_b32 s6, s6, 3
	s_add_u32 s6, s6, s8
	s_cmp_eq_u32 s18, 0
	s_cbranch_scc0 .Lopx_l1
	s_cmpk_lt_u32 s12, 0x110
	s_cbranch_scc0 .Lop_done
	s_mov_b32 s20, s6
	s_mul_hi_u32 s6, s20, 0x78787879
	s_lshr_b32 s6, s6, 4
	s_mul_i32 s7, s6, 34
	s_sub_u32 s7, s20, s7
	s_cmp_lt_u32 s7, 2
	s_cselect_b32 s21, 8, s6
	s_branch .Lop_decoded
.Lopx_l1:
	s_cmpk_lt_u32 s12, 0x100
	s_cbranch_scc0 .Lop_done
	s_lshr_b32 s21, s6, 5
	s_mul_i32 s7, s21, 34
	s_and_b32 s6, s6, 31
	s_add_u32 s20, s7, s6
	s_add_u32 s20, s20, 2
	s_branch .Lop_decoded
	s_cmp_eq_u32 s18, 0
	s_cbranch_scc0 .Lop_static
	s_barrier
	s_cmp_eq_u32 s10, 0
	s_cbranch_scc0 .Lop_fetch_wait
	s_mov_b64 s[6:7], exec
	s_mov_b64 exec, 1
	s_add_u32 s8, s96, 0x1da5d600
	s_addc_u32 s9, s97, 0
	v_mov_b32_e32 v112, 1
	v_mov_b32_e32 v113, 0
	global_atomic_add v114, v113, v112, s[8:9] sc0
	v_mov_b32_e32 v115, 0x125f0
	s_waitcnt vmcnt(0)
	ds_write_b32 v115, v114
	s_waitcnt lgkmcnt(0)
	s_mov_b64 exec, s[6:7]
